# k25 + rstd_prologue de-serialised at the start of G1/G2/Wup: all four units' row-statistic loads issued before one wait (was 4 serialized load-wait-sum groups)
# speedup vs baseline: 1.0088x; 1.0088x over previous
; #define LAS __attribute__((address_space(3)))
; __device__ __forceinline__ float rsqrtf_(float x) { return __builtin_amdgcn_rsqf(x); }
;     __device__ static __forceinline__ float rstd_of(const float* ssq, int row) {
;         const f32x4 a = *(const f32x4*)(ssq + (size_t)row * 16), b = *(const f32x4*)(ssq + (size_t)row * 16 + 4), c = *(const f32x4*)(ssq + (size_t)row * 16 + 8), d = *(const f32x4*)(ssq + (size_t)row * 16 + 12);
;         const float s = ((a.x + a.y) + (a.z + a.w)) + ((b.x + b.y) + (b.z + b.w)) + ((c.x + c.y) + (c.z + c.w)) + ((d.x + d.y) + (d.z + d.w));
;         return rsqrtf_(s * (1.0f / D) + EPS);
;     template <class Order>
;     __device__ static __forceinline__ void rstd_prologue(const float* ssq, const Order& S, int tid) {
;         LAS float* rsl = (LAS float*)((LAS unsigned char*)0 + pg8::STAGE_BYTES);
;         const int wv = __builtin_amdgcn_readfirstlane(tid >> 8), r = tid & 255;
;         float rs[4]; bool ok[4];
; #pragma unroll
;         for (int k = 0; k < 4; ++k) { pg8::Unit u; ok[k] = S.next(2 * k + wv, u); rs[k] = ok[k] ? rstd_of(ssq, u.pm * 256 + r) : 0.f; }
.LBB0_371:
	s_ashr_i32 s2, s4, 3
	s_add_i32 s2, s6, s2
	s_mul_hi_i32 s3, s2, 0x2aaaaaab
	s_lshr_b32 s4, s3, 31
	s_ashr_i32 s3, s3, 4
	s_add_i32 s3, s3, s4
	s_mul_i32 s4, s3, 0x60
	s_mul_i32 s3, s3, 6
	s_sub_i32 s2, s2, s4
	s_sub_i32 s4, 64, s3
	s_min_i32 s4, s4, 6
	s_abs_i32 s4, s4
	v_cvt_f32_u32_e32 v2, s4
	s_sub_i32 s6, 0, s4
	s_ashr_i32 s5, s2, 31
	s_abs_i32 s2, s2
	v_rcp_iflag_f32_e32 v2, v2
	s_nop 0
	v_mul_f32_e32 v2, 0x4f7ffffe, v2
	v_cvt_u32_f32_e32 v2, v2
	s_nop 0
	v_readfirstlane_b32 s7, v2
	s_mul_i32 s6, s6, s7
	s_mul_hi_u32 s6, s7, s6
	s_add_i32 s7, s7, s6
	s_mul_hi_u32 s6, s2, s7
	s_mul_i32 s6, s6, s4
	s_sub_i32 s2, s2, s6
	s_sub_i32 s6, s2, s4
	s_cmp_ge_u32 s2, s4
	s_cselect_b32 s2, s6, s2
	s_sub_i32 s6, s2, s4
	s_cmp_ge_u32 s2, s4
	s_cselect_b32 s2, s6, s2
	s_xor_b32 s2, s2, s5
	s_sub_i32 s2, s2, s5
	s_add_i32 s3, s3, s2
	v_lshl_or_b32 v26, s3, 8, v0
	v_ashrrev_i32_e32 v27, 31, v26
	v_readlane_b32 s2, v249, 26
	v_lshlrev_b64 v[26:27], 6, v[26:27]
	v_readlane_b32 s3, v249, 27
	s_nop 1
	v_lshl_add_u64 v[38:39], s[2:3], 0, v[26:27]
	global_load_dwordx4 v[26:29], v[38:39], off offset:48
	global_load_dwordx4 v[30:33], v[38:39], off offset:32
	global_load_dwordx4 v[34:37], v[38:39], off offset:16
	s_nop 0
	global_load_dwordx4 v[38:41], v[38:39], off

; #define LAS __attribute__((address_space(3)))
; __device__ __forceinline__ float rsqrtf_(float x) { return __builtin_amdgcn_rsqf(x); }
;     __device__ bool next(int i, Unit& u) const {
;         const long L = (long)i * G + c; if (L >= nwg) return false;
;         int wgid = (int)L; { const int q = nwg / NXCD, r = nwg % NXCD, xcd = wgid % NXCD, off = wgid / NXCD; wgid = (xcd < r ? xcd * (q + 1) : r * (q + 1) + (xcd - r) * q) + off; }
;         const int nig = WGM * nN, gid = wgid / nig, fm = gid * WGM, gsz = (nM - fm) < WGM ? (nM - fm) : WGM;
;         u.pm = fm + ((wgid % nig) % gsz); u.pn = (wgid % nig) / gsz; return true;
;     }
;     __device__ static __forceinline__ float rstd_of(const float* ssq, int row) {
;         const f32x4 a = *(const f32x4*)(ssq + (size_t)row * 16), b = *(const f32x4*)(ssq + (size_t)row * 16 + 4), c = *(const f32x4*)(ssq + (size_t)row * 16 + 8), d = *(const f32x4*)(ssq + (size_t)row * 16 + 12);
;         const float s = ((a.x + a.y) + (a.z + a.w)) + ((b.x + b.y) + (b.z + b.w)) + ((c.x + c.y) + (c.z + c.w)) + ((d.x + d.y) + (d.z + d.w));
;         return rsqrtf_(s * (1.0f / D) + EPS);
;     }
;     template <class Order>
;     __device__ static __forceinline__ void rstd_prologue(const float* ssq, const Order& S, int tid) {
;         LAS float* rsl = (LAS float*)((LAS unsigned char*)0 + pg8::STAGE_BYTES);
;         const int wv = __builtin_amdgcn_readfirstlane(tid >> 8), r = tid & 255;
;         float rs[4]; bool ok[4];
; #pragma unroll
;         for (int k = 0; k < 4; ++k) { pg8::Unit u; ok[k] = S.next(2 * k + wv, u); rs[k] = ok[k] ? rstd_of(ssq, u.pm * 256 + r) : 0.f; }
.LBB0_377:
	s_ashr_i32 s4, s6, 3
	s_add_i32 s4, s17, s4
	s_mul_hi_i32 s5, s4, 0x2aaaaaab
	s_lshr_b32 s6, s5, 31
	s_ashr_i32 s5, s5, 4
	s_add_i32 s5, s5, s6
	s_mul_i32 s6, s5, 0x60
	s_mul_i32 s5, s5, 6
	s_sub_i32 s4, s4, s6
	s_sub_i32 s6, 64, s5
	s_min_i32 s6, s6, 6
	s_abs_i32 s6, s6
	v_cvt_f32_u32_e32 v3, s6
	s_sub_i32 s10, 0, s6
	s_ashr_i32 s7, s4, 31
	s_abs_i32 s4, s4
	v_rcp_iflag_f32_e32 v3, v3
	s_nop 0
	v_mul_f32_e32 v3, 0x4f7ffffe, v3
	v_cvt_u32_f32_e32 v3, v3
	s_nop 0
	v_readfirstlane_b32 s11, v3
	s_mul_i32 s10, s10, s11
	s_mul_hi_u32 s10, s11, s10
	s_add_i32 s11, s11, s10
	s_mul_hi_u32 s10, s4, s11
	s_mul_i32 s10, s10, s6
	s_sub_i32 s4, s4, s10
	s_sub_i32 s10, s4, s6
	s_cmp_ge_u32 s4, s6
	s_cselect_b32 s4, s10, s4
	s_sub_i32 s10, s4, s6
	s_cmp_ge_u32 s4, s6
	s_cselect_b32 s4, s10, s4
	s_xor_b32 s4, s4, s7
	s_sub_i32 s4, s4, s7
	s_add_i32 s5, s5, s4
	v_lshl_or_b32 v44, s5, 8, v0
	v_ashrrev_i32_e32 v45, 31, v44
	v_readlane_b32 s4, v249, 26
	v_lshlrev_b64 v[44:45], 6, v[44:45]
	v_readlane_b32 s5, v249, 27
	s_nop 1
	v_lshl_add_u64 v[56:57], s[4:5], 0, v[44:45]
	global_load_dwordx4 v[44:47], v[56:57], off offset:48
	global_load_dwordx4 v[48:51], v[56:57], off offset:32
	global_load_dwordx4 v[52:55], v[56:57], off offset:16
	s_nop 0
	global_load_dwordx4 v[56:59], v[56:57], off

; #define LAS __attribute__((address_space(3)))
; __device__ __forceinline__ float rsqrtf_(float x) { return __builtin_amdgcn_rsqf(x); }
;     __device__ bool next(int i, Unit& u) const {
;         const long L = (long)i * G + c; if (L >= nwg) return false;
;         int wgid = (int)L; { const int q = nwg / NXCD, r = nwg % NXCD, xcd = wgid % NXCD, off = wgid / NXCD; wgid = (xcd < r ? xcd * (q + 1) : r * (q + 1) + (xcd - r) * q) + off; }
;         const int nig = WGM * nN, gid = wgid / nig, fm = gid * WGM, gsz = (nM - fm) < WGM ? (nM - fm) : WGM;
;         u.pm = fm + ((wgid % nig) % gsz); u.pn = (wgid % nig) / gsz; return true;
;     }
;     __device__ static __forceinline__ float rstd_of(const float* ssq, int row) {
;         const f32x4 a = *(const f32x4*)(ssq + (size_t)row * 16), b = *(const f32x4*)(ssq + (size_t)row * 16 + 4), c = *(const f32x4*)(ssq + (size_t)row * 16 + 8), d = *(const f32x4*)(ssq + (size_t)row * 16 + 12);
;         const float s = ((a.x + a.y) + (a.z + a.w)) + ((b.x + b.y) + (b.z + b.w)) + ((c.x + c.y) + (c.z + c.w)) + ((d.x + d.y) + (d.z + d.w));
;         return rsqrtf_(s * (1.0f / D) + EPS);
;     }
;     template <class Order>
;     __device__ static __forceinline__ void rstd_prologue(const float* ssq, const Order& S, int tid) {
;         LAS float* rsl = (LAS float*)((LAS unsigned char*)0 + pg8::STAGE_BYTES);
;         const int wv = __builtin_amdgcn_readfirstlane(tid >> 8), r = tid & 255;
;         float rs[4]; bool ok[4];
; #pragma unroll
;         for (int k = 0; k < 4; ++k) { pg8::Unit u; ok[k] = S.next(2 * k + wv, u); rs[k] = ok[k] ? rstd_of(ssq, u.pm * 256 + r) : 0.f; }
.LBB0_383:
	s_ashr_i32 s6, s17, 3
	s_add_i32 s6, s27, s6
	s_mul_hi_i32 s7, s6, 0x2aaaaaab
	s_lshr_b32 s10, s7, 31
	s_ashr_i32 s7, s7, 4
	s_add_i32 s7, s7, s10
	s_mul_i32 s10, s7, 0x60
	s_mul_i32 s7, s7, 6
	s_sub_i32 s6, s6, s10
	s_sub_i32 s10, 64, s7
	s_min_i32 s10, s10, 6
	s_abs_i32 s10, s10
	v_cvt_f32_u32_e32 v4, s10
	s_sub_i32 s17, 0, s10
	s_ashr_i32 s11, s6, 31
	s_abs_i32 s6, s6
	v_rcp_iflag_f32_e32 v4, v4
	s_nop 0
	v_mul_f32_e32 v4, 0x4f7ffffe, v4
	v_cvt_u32_f32_e32 v4, v4
	s_nop 0
	v_readfirstlane_b32 s26, v4
	s_mul_i32 s17, s17, s26
	s_mul_hi_u32 s17, s26, s17
	s_add_i32 s26, s26, s17
	s_mul_hi_u32 s17, s6, s26
	s_mul_i32 s17, s17, s10
	s_sub_i32 s6, s6, s17
	s_sub_i32 s17, s6, s10
	s_cmp_ge_u32 s6, s10
	s_cselect_b32 s6, s17, s6
	s_sub_i32 s17, s6, s10
	s_cmp_ge_u32 s6, s10
	s_cselect_b32 s6, s17, s6
	s_xor_b32 s6, s6, s11
	s_sub_i32 s6, s6, s11
	s_add_i32 s7, s7, s6
	v_lshl_or_b32 v62, s7, 8, v0
	v_ashrrev_i32_e32 v63, 31, v62
	v_readlane_b32 s6, v249, 26
	v_lshlrev_b64 v[62:63], 6, v[62:63]
	v_readlane_b32 s7, v249, 27
	s_nop 1
	v_lshl_add_u64 v[74:75], s[6:7], 0, v[62:63]
	global_load_dwordx4 v[62:65], v[74:75], off offset:48
	global_load_dwordx4 v[66:69], v[74:75], off offset:32
	global_load_dwordx4 v[70:73], v[74:75], off offset:16
	s_nop 0
	global_load_dwordx4 v[74:77], v[74:75], off

; #define LAS __attribute__((address_space(3)))
; __device__ __forceinline__ float rsqrtf_(float x) { return __builtin_amdgcn_rsqf(x); }
;     __device__ bool next(int i, Unit& u) const {
;         const long L = (long)i * G + c; if (L >= nwg) return false;
;         int wgid = (int)L; { const int q = nwg / NXCD, r = nwg % NXCD, xcd = wgid % NXCD, off = wgid / NXCD; wgid = (xcd < r ? xcd * (q + 1) : r * (q + 1) + (xcd - r) * q) + off; }
;         const int nig = WGM * nN, gid = wgid / nig, fm = gid * WGM, gsz = (nM - fm) < WGM ? (nM - fm) : WGM;
;         u.pm = fm + ((wgid % nig) % gsz); u.pn = (wgid % nig) / gsz; return true;
;     }
;     __device__ static __forceinline__ float rstd_of(const float* ssq, int row) {
;         const f32x4 a = *(const f32x4*)(ssq + (size_t)row * 16), b = *(const f32x4*)(ssq + (size_t)row * 16 + 4), c = *(const f32x4*)(ssq + (size_t)row * 16 + 8), d = *(const f32x4*)(ssq + (size_t)row * 16 + 12);
;         const float s = ((a.x + a.y) + (a.z + a.w)) + ((b.x + b.y) + (b.z + b.w)) + ((c.x + c.y) + (c.z + c.w)) + ((d.x + d.y) + (d.z + d.w));
;         return rsqrtf_(s * (1.0f / D) + EPS);
;     }
;     template <class Order>
;     __device__ static __forceinline__ void rstd_prologue(const float* ssq, const Order& S, int tid) {
;         LAS float* rsl = (LAS float*)((LAS unsigned char*)0 + pg8::STAGE_BYTES);
;         const int wv = __builtin_amdgcn_readfirstlane(tid >> 8), r = tid & 255;
;         float rs[4]; bool ok[4];
; #pragma unroll
;         for (int k = 0; k < 4; ++k) { pg8::Unit u; ok[k] = S.next(2 * k + wv, u); rs[k] = ok[k] ? rstd_of(ssq, u.pm * 256 + r) : 0.f; }
; #pragma unroll
;         for (int k = 0; k < 4; ++k) if (ok[k]) rsl[(2 * k + wv) * 256 + r] = rs[k];
.LBB0_389:
	s_ashr_i32 s10, s16, 3
	s_add_i32 s10, s31, s10
	s_mul_hi_i32 s11, s10, 0x2aaaaaab
	s_lshr_b32 s16, s11, 31
	s_ashr_i32 s11, s11, 4
	s_add_i32 s11, s11, s16
	s_mul_i32 s16, s11, 0x60
	s_mul_i32 s11, s11, 6
	s_sub_i32 s10, s10, s16
	s_sub_i32 s16, 64, s11
	s_min_i32 s16, s16, 6
	s_abs_i32 s16, s16
	v_cvt_f32_u32_e32 v5, s16
	s_sub_i32 s26, 0, s16
	s_ashr_i32 s17, s10, 31
	s_abs_i32 s10, s10
	v_rcp_iflag_f32_e32 v5, v5
	s_nop 0
	v_mul_f32_e32 v5, 0x4f7ffffe, v5
	v_cvt_u32_f32_e32 v5, v5
	s_nop 0
	v_readfirstlane_b32 s27, v5
	s_mul_i32 s26, s26, s27
	s_mul_hi_u32 s26, s27, s26
	s_add_i32 s27, s27, s26
	s_mul_hi_u32 s26, s10, s27
	s_mul_i32 s26, s26, s16
	s_sub_i32 s10, s10, s26
	s_sub_i32 s26, s10, s16
	s_cmp_ge_u32 s10, s16
	s_cselect_b32 s10, s26, s10
	s_sub_i32 s26, s10, s16
	s_cmp_ge_u32 s10, s16
	s_cselect_b32 s10, s26, s10
	s_xor_b32 s10, s10, s17
	s_sub_i32 s10, s10, s17
	s_add_i32 s11, s11, s10
	v_lshl_or_b32 v80, s11, 8, v0
	v_ashrrev_i32_e32 v81, 31, v80
	v_readlane_b32 s10, v249, 26
	v_lshlrev_b64 v[80:81], 6, v[80:81]
	v_readlane_b32 s11, v249, 27
	s_nop 1
	v_lshl_add_u64 v[92:93], s[10:11], 0, v[80:81]
	global_load_dwordx4 v[80:83], v[92:93], off offset:48
	global_load_dwordx4 v[84:87], v[92:93], off offset:32
	global_load_dwordx4 v[88:91], v[92:93], off offset:16
	s_nop 0
	global_load_dwordx4 v[92:95], v[92:93], off
.LBB0_390:
	s_waitcnt vmcnt(0)
	s_andn2_b64 vcc, exec, s[0:1]
	s_cbranch_vccnz .Lrs0_0
	v_add_f32_e32 v30, v30, v31
	v_add_f32_e32 v32, v32, v33
	v_mov_b32_e32 v42, v39
	v_mov_b32_e32 v43, v40
	v_mov_b32_e32 v39, v41
	v_mov_b32_e32 v40, v35
	v_mov_b32_e32 v41, v36
	v_mov_b32_e32 v35, v37
	v_pk_add_f32 v[38:39], v[42:43], v[38:39]
	v_pk_add_f32 v[34:35], v[40:41], v[34:35]
	v_pk_add_f32 v[38:39], v[38:39], v[38:39] op_sel:[0,1] op_sel_hi:[1,0]
	v_pk_add_f32 v[34:35], v[34:35], v[34:35] op_sel:[0,1] op_sel_hi:[1,0]
	v_mov_b32_e32 v39, v26
	v_mov_b32_e32 v35, v27
	v_mov_b32_e32 v31, v28
	v_mov_b32_e32 v33, v29
	v_pk_add_f32 v[26:27], v[38:39], v[34:35]
	v_pk_add_f32 v[28:29], v[30:31], v[32:33]
	s_nop 0
	v_pk_add_f32 v[26:27], v[26:27], v[28:29]
	s_nop 0
	v_add_f32_e32 v2, v26, v27
	v_fmamk_f32 v2, v2, 0x3a800000, v204
	v_rsq_f32_e32 v2, v2
.Lrs0_0:
	s_andn2_b64 vcc, exec, s[2:3]
	s_cbranch_vccnz .Lrs0_1
	v_add_f32_e32 v48, v48, v49
	v_add_f32_e32 v50, v50, v51
	v_mov_b32_e32 v60, v57
	v_mov_b32_e32 v61, v58
	v_mov_b32_e32 v57, v59
	v_mov_b32_e32 v58, v53
	v_mov_b32_e32 v59, v54
	v_mov_b32_e32 v53, v55
	v_pk_add_f32 v[56:57], v[60:61], v[56:57]
	v_pk_add_f32 v[52:53], v[58:59], v[52:53]
	v_pk_add_f32 v[56:57], v[56:57], v[56:57] op_sel:[0,1] op_sel_hi:[1,0]
	v_pk_add_f32 v[52:53], v[52:53], v[52:53] op_sel:[0,1] op_sel_hi:[1,0]
	v_mov_b32_e32 v57, v44
	v_mov_b32_e32 v53, v45
	v_mov_b32_e32 v49, v46
	v_mov_b32_e32 v51, v47
	v_pk_add_f32 v[44:45], v[56:57], v[52:53]
	v_pk_add_f32 v[46:47], v[48:49], v[50:51]
	s_nop 0
	v_pk_add_f32 v[44:45], v[44:45], v[46:47]
	s_nop 0
	v_add_f32_e32 v3, v44, v45
	v_fmamk_f32 v3, v3, 0x3a800000, v204
	v_rsq_f32_e32 v3, v3
.Lrs0_1:
	s_andn2_b64 vcc, exec, s[4:5]
	s_cbranch_vccnz .Lrs0_2
	v_add_f32_e32 v66, v66, v67
	v_add_f32_e32 v68, v68, v69
	v_mov_b32_e32 v78, v75
	v_mov_b32_e32 v79, v76
	v_mov_b32_e32 v75, v77
	v_mov_b32_e32 v76, v71
	v_mov_b32_e32 v77, v72
	v_mov_b32_e32 v71, v73
	v_pk_add_f32 v[74:75], v[78:79], v[74:75]
	v_pk_add_f32 v[70:71], v[76:77], v[70:71]
	v_pk_add_f32 v[74:75], v[74:75], v[74:75] op_sel:[0,1] op_sel_hi:[1,0]
	v_pk_add_f32 v[70:71], v[70:71], v[70:71] op_sel:[0,1] op_sel_hi:[1,0]
	v_mov_b32_e32 v75, v62
	v_mov_b32_e32 v71, v63
	v_mov_b32_e32 v67, v64
	v_mov_b32_e32 v69, v65
	v_pk_add_f32 v[62:63], v[74:75], v[70:71]
	v_pk_add_f32 v[64:65], v[66:67], v[68:69]
	s_nop 0
	v_pk_add_f32 v[62:63], v[62:63], v[64:65]
	s_nop 0
	v_add_f32_e32 v4, v62, v63
	v_fmamk_f32 v4, v4, 0x3a800000, v204
	v_rsq_f32_e32 v4, v4
.Lrs0_2:
	s_andn2_b64 vcc, exec, s[6:7]
	s_cbranch_vccnz .Lrs0_3
	v_add_f32_e32 v84, v84, v85
	v_add_f32_e32 v86, v86, v87
	v_mov_b32_e32 v96, v93
	v_mov_b32_e32 v97, v94
	v_mov_b32_e32 v93, v95
	v_mov_b32_e32 v94, v89
	v_mov_b32_e32 v95, v90
	v_mov_b32_e32 v89, v91
	v_pk_add_f32 v[92:93], v[96:97], v[92:93]
	v_pk_add_f32 v[88:89], v[94:95], v[88:89]
	v_pk_add_f32 v[92:93], v[92:93], v[92:93] op_sel:[0,1] op_sel_hi:[1,0]
	v_pk_add_f32 v[88:89], v[88:89], v[88:89] op_sel:[0,1] op_sel_hi:[1,0]
	v_mov_b32_e32 v93, v80
	v_mov_b32_e32 v89, v81
	v_mov_b32_e32 v85, v82
	v_mov_b32_e32 v87, v83
	v_pk_add_f32 v[80:81], v[92:93], v[88:89]
	v_pk_add_f32 v[82:83], v[84:85], v[86:87]
	s_nop 0
	v_pk_add_f32 v[80:81], v[80:81], v[82:83]
	s_nop 0
	v_add_f32_e32 v5, v80, v81
	v_fmamk_f32 v5, v5, 0x3a800000, v204
	v_rsq_f32_e32 v5, v5

; #define LAS __attribute__((address_space(3)))
;     __device__ bool next(int i, Unit& u) const {
;         const long L = (long)i * G + c; if (L >= nwg) return false;
;         int wgid = (int)L; { const int q = nwg / NXCD, r = nwg % NXCD, xcd = wgid % NXCD, off = wgid / NXCD; wgid = (xcd < r ? xcd * (q + 1) : r * (q + 1) + (xcd - r) * q) + off; }
;         const int nig = WGM * nN, gid = wgid / nig, fm = gid * WGM, gsz = (nM - fm) < WGM ? (nM - fm) : WGM;
;         u.pm = fm + ((wgid % nig) % gsz); u.pn = (wgid % nig) / gsz; return true;
;     }
;     template <class Order>
;     __device__ static __forceinline__ void rstd_prologue(const float* ssq, const Order& S, int tid) {
;         LAS float* rsl = (LAS float*)((LAS unsigned char*)0 + pg8::STAGE_BYTES);
;         const int wv = __builtin_amdgcn_readfirstlane(tid >> 8), r = tid & 255;
;         float rs[4]; bool ok[4];
; #pragma unroll
;         for (int k = 0; k < 4; ++k) { pg8::Unit u; ok[k] = S.next(2 * k + wv, u); rs[k] = ok[k] ? rstd_of(ssq, u.pm * 256 + r) : 0.f; }
.LBB0_921:
	v_mov_b32_e32 v146, v248
	v_readlane_b32 s0, v249, 28
	v_readlane_b32 s1, v249, 2
	v_readlane_b32 s2, v249, 3
	v_add_u32_e32 v0, s0, v146
	s_waitcnt lgkmcnt(1)
	v_mov_b64_e32 v[4:5], s[10:11]
	v_readfirstlane_b32 s8, v0
	s_ashr_i32 s9, s8, 8
	s_mul_hi_i32 s0, s9, s1
	s_mul_i32 s1, s9, s1
	s_add_u32 s2, s1, s2
	v_readlane_b32 s1, v252, 18
	s_addc_u32 s3, s0, s1
	v_cmp_ge_i64_e32 vcc, s[2:3], v[4:5]
	v_and_b32_e32 v2, 0xff, v0
	v_cmp_lt_i64_e64 s[0:1], s[2:3], v[4:5]
	v_mov_b32_e32 v3, 0
	v_mov_b32_e32 v4, 0
	s_cbranch_vccnz .LBB0_923
	s_ashr_i32 s3, s2, 31
	s_lshr_b32 s3, s3, 29
	s_add_i32 s3, s2, s3
	s_ashr_i32 s4, s3, 3
	s_and_b32 s3, s3, -8
	s_sub_i32 s2, s2, s3
	s_cmp_lt_i32 s2, 0
	v_readlane_b32 s3, v255, 25
	v_readlane_b32 s5, v255, 27
	s_cselect_b32 s3, s5, s3
	s_mul_i32 s2, s3, s2
	s_add_i32 s2, s2, s4
	s_mul_hi_i32 s3, s2, 0x88888889
	s_add_i32 s3, s3, s2
	s_lshr_b32 s4, s3, 31
	s_ashr_i32 s3, s3, 6
	s_add_i32 s3, s3, s4
	s_mul_i32 s4, s3, 0x78
	s_sub_i32 s2, s2, s4
	s_mul_i32 s3, s3, 6
	v_readlane_b32 s4, v255, 23
	s_sub_i32 s4, s4, s3
	s_min_i32 s4, s4, 6
	s_abs_i32 s4, s4
	v_cvt_f32_u32_e32 v4, s4
	s_sub_i32 s6, 0, s4
	s_ashr_i32 s5, s2, 31
	s_abs_i32 s2, s2
	v_rcp_iflag_f32_e32 v4, v4
	s_nop 0
	v_mul_f32_e32 v4, 0x4f7ffffe, v4
	v_cvt_u32_f32_e32 v4, v4
	s_nop 0
	v_readfirstlane_b32 s7, v4
	s_mul_i32 s6, s6, s7
	s_mul_hi_u32 s6, s7, s6
	s_add_i32 s7, s7, s6
	s_mul_hi_u32 s6, s2, s7
	s_mul_i32 s6, s6, s4
	s_sub_i32 s2, s2, s6
	s_sub_i32 s6, s2, s4
	s_cmp_ge_u32 s2, s4
	s_cselect_b32 s2, s6, s2
	s_sub_i32 s6, s2, s4
	s_cmp_ge_u32 s2, s4
	s_cselect_b32 s2, s6, s2
	s_xor_b32 s2, s2, s5
	s_sub_i32 s2, s2, s5
	s_add_i32 s2, s2, s3
	v_lshl_or_b32 v26, s2, 8, v2
	v_ashrrev_i32_e32 v27, 31, v26
	v_readlane_b32 s2, v249, 26
	v_lshlrev_b64 v[26:27], 6, v[26:27]
	v_readlane_b32 s3, v249, 27
	s_nop 1
	v_lshl_add_u64 v[38:39], s[2:3], 0, v[26:27]
	s_waitcnt lgkmcnt(0)
	global_load_dwordx4 v[26:29], v[38:39], off offset:48
	global_load_dwordx4 v[30:33], v[38:39], off offset:32
	global_load_dwordx4 v[34:37], v[38:39], off offset:16
	s_nop 0
	global_load_dwordx4 v[38:41], v[38:39], off
.LBB0_923:
	s_add_i32 s2, s9, 2
	v_readlane_b32 s4, v249, 2
	s_mul_hi_i32 s3, s2, s4
	s_mul_i32 s2, s2, s4
	v_readlane_b32 s4, v249, 3
	s_add_u32 s4, s2, s4
	v_readlane_b32 s2, v252, 18
	s_addc_u32 s5, s3, s2
	s_waitcnt lgkmcnt(0)
	v_mov_b64_e32 v[6:7], s[10:11]
	v_cmp_ge_i64_e32 vcc, s[4:5], v[6:7]
	v_cmp_lt_i64_e64 s[2:3], s[4:5], v[6:7]
	s_cbranch_vccnz .LBB0_925
	s_ashr_i32 s5, s4, 31
	s_lshr_b32 s5, s5, 29
	s_add_i32 s5, s4, s5
	s_ashr_i32 s6, s5, 3
	s_and_b32 s5, s5, -8
	s_sub_i32 s4, s4, s5
	s_cmp_lt_i32 s4, 0
	v_readlane_b32 s5, v255, 25
	v_readlane_b32 s7, v255, 27
	s_cselect_b32 s5, s7, s5
	s_mul_i32 s4, s5, s4
	s_add_i32 s4, s4, s6
	s_mul_hi_i32 s5, s4, 0x88888889
	s_add_i32 s5, s5, s4
	s_lshr_b32 s6, s5, 31
	s_ashr_i32 s5, s5, 6
	s_add_i32 s5, s5, s6
	s_mul_i32 s6, s5, 0x78
	s_sub_i32 s4, s4, s6
	s_mul_i32 s5, s5, 6
	v_readlane_b32 s6, v255, 23
	s_sub_i32 s6, s6, s5
	s_min_i32 s6, s6, 6
	s_abs_i32 s6, s6
	v_cvt_f32_u32_e32 v3, s6
	s_sub_i32 s16, 0, s6
	s_ashr_i32 s7, s4, 31
	s_abs_i32 s4, s4
	v_rcp_iflag_f32_e32 v3, v3
	s_nop 0
	v_mul_f32_e32 v3, 0x4f7ffffe, v3
	v_cvt_u32_f32_e32 v3, v3
	s_nop 0
	v_readfirstlane_b32 s17, v3
	s_mul_i32 s16, s16, s17
	s_mul_hi_u32 s16, s17, s16
	s_add_i32 s17, s17, s16
	s_mul_hi_u32 s16, s4, s17
	s_mul_i32 s16, s16, s6
	s_sub_i32 s4, s4, s16
	s_sub_i32 s16, s4, s6
	s_cmp_ge_u32 s4, s6
	s_cselect_b32 s4, s16, s4
	s_sub_i32 s16, s4, s6
	s_cmp_ge_u32 s4, s6
	s_cselect_b32 s4, s16, s4
	s_xor_b32 s4, s4, s7
	s_sub_i32 s4, s4, s7
	s_add_i32 s4, s4, s5
	v_lshl_or_b32 v44, s4, 8, v2
	v_ashrrev_i32_e32 v45, 31, v44
	v_readlane_b32 s4, v249, 26
	v_lshlrev_b64 v[44:45], 6, v[44:45]
	v_readlane_b32 s5, v249, 27
	s_nop 1
	v_lshl_add_u64 v[56:57], s[4:5], 0, v[44:45]
	global_load_dwordx4 v[44:47], v[56:57], off offset:48
	global_load_dwordx4 v[48:51], v[56:57], off offset:32
	global_load_dwordx4 v[52:55], v[56:57], off offset:16
	s_nop 0
	global_load_dwordx4 v[56:59], v[56:57], off
; #define LAS __attribute__((address_space(3)))
; __device__ __forceinline__ float rsqrtf_(float x) { return __builtin_amdgcn_rsqf(x); }
;     __device__ bool next(int i, Unit& u) const {
;         const long L = (long)i * G + c; if (L >= nwg) return false;
;         int wgid = (int)L; { const int q = nwg / NXCD, r = nwg % NXCD, xcd = wgid % NXCD, off = wgid / NXCD; wgid = (xcd < r ? xcd * (q + 1) : r * (q + 1) + (xcd - r) * q) + off; }
;         const int nig = WGM * nN, gid = wgid / nig, fm = gid * WGM, gsz = (nM - fm) < WGM ? (nM - fm) : WGM;
;         u.pm = fm + ((wgid % nig) % gsz); u.pn = (wgid % nig) / gsz; return true;
;     }
;     __device__ static __forceinline__ float rstd_of(const float* ssq, int row) {
;         const f32x4 a = *(const f32x4*)(ssq + (size_t)row * 16), b = *(const f32x4*)(ssq + (size_t)row * 16 + 4), c = *(const f32x4*)(ssq + (size_t)row * 16 + 8), d = *(const f32x4*)(ssq + (size_t)row * 16 + 12);
;         const float s = ((a.x + a.y) + (a.z + a.w)) + ((b.x + b.y) + (b.z + b.w)) + ((c.x + c.y) + (c.z + c.w)) + ((d.x + d.y) + (d.z + d.w));
;         return rsqrtf_(s * (1.0f / D) + EPS);
;     }
;     template <class Order>
;     __device__ static __forceinline__ void rstd_prologue(const float* ssq, const Order& S, int tid) {
;         LAS float* rsl = (LAS float*)((LAS unsigned char*)0 + pg8::STAGE_BYTES);
;         const int wv = __builtin_amdgcn_readfirstlane(tid >> 8), r = tid & 255;
;         float rs[4]; bool ok[4];
; #pragma unroll
;         for (int k = 0; k < 4; ++k) { pg8::Unit u; ok[k] = S.next(2 * k + wv, u); rs[k] = ok[k] ? rstd_of(ssq, u.pm * 256 + r) : 0.f; }
; #pragma unroll
;         for (int k = 0; k < 4; ++k) if (ok[k]) rsl[(2 * k + wv) * 256 + r] = rs[k];
.LBB0_925:
	s_add_i32 s4, s9, 4
	v_readlane_b32 s6, v249, 2
	s_mul_hi_i32 s5, s4, s6
	s_mul_i32 s4, s4, s6
	v_readlane_b32 s6, v249, 3
	s_add_u32 s6, s4, s6
	v_readlane_b32 s4, v252, 18
	s_addc_u32 s7, s5, s4
	v_mov_b64_e32 v[6:7], s[10:11]
	v_cmp_ge_i64_e32 vcc, s[6:7], v[6:7]
	v_cmp_lt_i64_e64 s[4:5], s[6:7], v[6:7]
	v_mov_b32_e32 v5, 0
	v_mov_b32_e32 v6, 0
	s_cbranch_vccnz .LBB0_927
	s_ashr_i32 s7, s6, 31
	s_lshr_b32 s7, s7, 29
	s_add_i32 s7, s6, s7
	s_ashr_i32 s16, s7, 3
	s_and_b32 s7, s7, -8
	s_sub_i32 s6, s6, s7
	s_cmp_lt_i32 s6, 0
	v_readlane_b32 s7, v255, 25
	v_readlane_b32 s17, v255, 27
	s_cselect_b32 s7, s17, s7
	s_mul_i32 s6, s7, s6
	s_add_i32 s6, s6, s16
	s_mul_hi_i32 s7, s6, 0x88888889
	s_add_i32 s7, s7, s6
	s_lshr_b32 s16, s7, 31
	s_ashr_i32 s7, s7, 6
	s_add_i32 s7, s7, s16
	s_mul_i32 s16, s7, 0x78
	s_sub_i32 s6, s6, s16
	s_mul_i32 s7, s7, 6
	v_readlane_b32 s16, v255, 23
	s_sub_i32 s16, s16, s7
	s_min_i32 s16, s16, 6
	s_abs_i32 s16, s16
	v_cvt_f32_u32_e32 v6, s16
	s_sub_i32 s26, 0, s16
	s_ashr_i32 s17, s6, 31
	s_abs_i32 s6, s6
	v_rcp_iflag_f32_e32 v6, v6
	s_nop 0
	v_mul_f32_e32 v6, 0x4f7ffffe, v6
	v_cvt_u32_f32_e32 v6, v6
	s_nop 0
	v_readfirstlane_b32 s27, v6
	s_mul_i32 s26, s26, s27
	s_mul_hi_u32 s26, s27, s26
	s_add_i32 s27, s27, s26
	s_mul_hi_u32 s26, s6, s27
	s_mul_i32 s26, s26, s16
	s_sub_i32 s6, s6, s26
	s_sub_i32 s26, s6, s16
	s_cmp_ge_u32 s6, s16
	s_cselect_b32 s6, s26, s6
	s_sub_i32 s26, s6, s16
	s_cmp_ge_u32 s6, s16
	s_cselect_b32 s6, s26, s6
	s_xor_b32 s6, s6, s17
	s_sub_i32 s6, s6, s17
	s_add_i32 s6, s6, s7
	v_lshl_or_b32 v62, s6, 8, v2
	v_ashrrev_i32_e32 v63, 31, v62
	v_readlane_b32 s6, v249, 26
	v_lshlrev_b64 v[62:63], 6, v[62:63]
	v_readlane_b32 s7, v249, 27
	s_nop 1
	v_lshl_add_u64 v[74:75], s[6:7], 0, v[62:63]
	global_load_dwordx4 v[62:65], v[74:75], off offset:48
	global_load_dwordx4 v[66:69], v[74:75], off offset:32
	global_load_dwordx4 v[70:73], v[74:75], off offset:16
	s_nop 0
	global_load_dwordx4 v[74:77], v[74:75], off
.LBB0_927:
	s_add_i32 s6, s9, 6
	v_readlane_b32 s9, v249, 2
	s_mul_hi_i32 s7, s6, s9
	s_mul_i32 s6, s6, s9
	v_readlane_b32 s9, v249, 3
	s_add_u32 s26, s6, s9
	v_readlane_b32 s6, v252, 18
	s_addc_u32 s27, s7, s6
	v_mov_b64_e32 v[8:9], s[10:11]
	v_cmp_ge_i64_e32 vcc, s[26:27], v[8:9]
	v_cmp_lt_i64_e64 s[6:7], s[26:27], v[8:9]
	s_cbranch_vccnz .LBB0_929
	s_ashr_i32 s9, s26, 31
	s_lshr_b32 s9, s9, 29
	s_add_i32 s9, s26, s9
	s_ashr_i32 s16, s9, 3
	s_and_b32 s9, s9, -8
	s_sub_i32 s9, s26, s9
	s_cmp_lt_i32 s9, 0
	v_readlane_b32 s17, v255, 25
	v_readlane_b32 s26, v255, 27
	s_cselect_b32 s17, s26, s17
	s_mul_i32 s9, s17, s9
	s_add_i32 s9, s9, s16
	s_mul_hi_i32 s16, s9, 0x88888889
	s_add_i32 s16, s16, s9
	s_lshr_b32 s17, s16, 31
	s_ashr_i32 s16, s16, 6
	s_add_i32 s16, s16, s17
	s_mul_i32 s17, s16, 0x78
	s_sub_i32 s9, s9, s17
	s_mul_i32 s16, s16, 6
	v_readlane_b32 s17, v255, 23
	s_sub_i32 s17, s17, s16
	s_min_i32 s17, s17, 6
	s_abs_i32 s17, s17
	v_cvt_f32_u32_e32 v5, s17
	s_sub_i32 s27, 0, s17
	s_ashr_i32 s26, s9, 31
	s_abs_i32 s9, s9
	v_rcp_iflag_f32_e32 v5, v5
	s_nop 0
	v_mul_f32_e32 v5, 0x4f7ffffe, v5
	v_cvt_u32_f32_e32 v5, v5
	s_nop 0
	v_readfirstlane_b32 s28, v5
	s_mul_i32 s27, s27, s28
	s_mul_hi_u32 s27, s28, s27
	s_add_i32 s28, s28, s27
	s_mul_hi_u32 s27, s9, s28
	s_mul_i32 s27, s27, s17
	s_sub_i32 s9, s9, s27
	s_sub_i32 s27, s9, s17
	s_cmp_ge_u32 s9, s17
	s_cselect_b32 s9, s27, s9
	s_sub_i32 s27, s9, s17
	s_cmp_ge_u32 s9, s17
	s_cselect_b32 s9, s27, s9
	s_xor_b32 s9, s9, s26
	s_sub_i32 s9, s9, s26
	s_add_i32 s9, s9, s16
	v_lshl_or_b32 v80, s9, 8, v2
	v_ashrrev_i32_e32 v81, 31, v80
	v_readlane_b32 s16, v249, 26
	v_lshlrev_b64 v[80:81], 6, v[80:81]
	v_readlane_b32 s17, v249, 27
	s_nop 1
	v_lshl_add_u64 v[92:93], s[16:17], 0, v[80:81]
	global_load_dwordx4 v[80:83], v[92:93], off offset:48
	global_load_dwordx4 v[84:87], v[92:93], off offset:32
	global_load_dwordx4 v[88:91], v[92:93], off offset:16
	s_nop 0
	global_load_dwordx4 v[92:95], v[92:93], off
.LBB0_929:
	s_waitcnt vmcnt(0)
	s_andn2_b64 vcc, exec, s[0:1]
	s_cbranch_vccnz .Lrs1_0
	v_add_f32_e32 v30, v30, v31
	v_add_f32_e32 v32, v32, v33
	v_mov_b32_e32 v42, v39
	v_mov_b32_e32 v43, v40
	v_mov_b32_e32 v39, v41
	v_mov_b32_e32 v40, v35
	v_mov_b32_e32 v41, v36
	v_mov_b32_e32 v35, v37
	v_pk_add_f32 v[38:39], v[42:43], v[38:39]
	v_pk_add_f32 v[34:35], v[40:41], v[34:35]
	v_pk_add_f32 v[38:39], v[38:39], v[38:39] op_sel:[0,1] op_sel_hi:[1,0]
	v_pk_add_f32 v[34:35], v[34:35], v[34:35] op_sel:[0,1] op_sel_hi:[1,0]
	v_mov_b32_e32 v39, v26
	v_mov_b32_e32 v35, v27
	v_mov_b32_e32 v31, v28
	v_mov_b32_e32 v33, v29
	v_pk_add_f32 v[26:27], v[38:39], v[34:35]
	v_pk_add_f32 v[28:29], v[30:31], v[32:33]
	s_nop 0
	v_pk_add_f32 v[26:27], v[26:27], v[28:29]
	s_nop 0
	v_add_f32_e32 v4, v26, v27
	v_fmamk_f32 v4, v4, 0x3a800000, v204
	v_rsq_f32_e32 v4, v4

; __device__ __forceinline__ float rsqrtf_(float x) { return __builtin_amdgcn_rsqf(x); }
;     __device__ static __forceinline__ float rstd_of(const float* ssq, int row) {
;         const f32x4 a = *(const f32x4*)(ssq + (size_t)row * 16), b = *(const f32x4*)(ssq + (size_t)row * 16 + 4), c = *(const f32x4*)(ssq + (size_t)row * 16 + 8), d = *(const f32x4*)(ssq + (size_t)row * 16 + 12);
;         const float s = ((a.x + a.y) + (a.z + a.w)) + ((b.x + b.y) + (b.z + b.w)) + ((c.x + c.y) + (c.z + c.w)) + ((d.x + d.y) + (d.z + d.w));
;         return rsqrtf_(s * (1.0f / D) + EPS);
;     template <class Order>
;     __device__ static __forceinline__ void rstd_prologue(const float* ssq, const Order& S, int tid) {
;     ...
;         for (int k = 0; k < 4; ++k) { pg8::Unit u; ok[k] = S.next(2 * k + wv, u); rs[k] = ok[k] ? rstd_of(ssq, u.pm * 256 + r) : 0.f; }
.Lrs1_1:
	s_andn2_b64 vcc, exec, s[4:5]
	s_cbranch_vccnz .Lrs1_2
	v_add_f32_e32 v66, v66, v67
	v_add_f32_e32 v68, v68, v69
	v_mov_b32_e32 v78, v75
	v_mov_b32_e32 v79, v76
	v_mov_b32_e32 v75, v77
	v_mov_b32_e32 v76, v71
	v_mov_b32_e32 v77, v72
	v_mov_b32_e32 v71, v73
	v_pk_add_f32 v[74:75], v[78:79], v[74:75]
	v_pk_add_f32 v[70:71], v[76:77], v[70:71]
	v_pk_add_f32 v[74:75], v[74:75], v[74:75] op_sel:[0,1] op_sel_hi:[1,0]
	v_pk_add_f32 v[70:71], v[70:71], v[70:71] op_sel:[0,1] op_sel_hi:[1,0]
	v_mov_b32_e32 v75, v62
	v_mov_b32_e32 v71, v63
	v_mov_b32_e32 v67, v64
	v_mov_b32_e32 v69, v65
	v_pk_add_f32 v[62:63], v[74:75], v[70:71]
	v_pk_add_f32 v[64:65], v[66:67], v[68:69]
	s_nop 0
	v_pk_add_f32 v[62:63], v[62:63], v[64:65]
	s_nop 0
	v_add_f32_e32 v6, v62, v63
	v_fmamk_f32 v6, v6, 0x3a800000, v204
	v_rsq_f32_e32 v6, v6

; #define LAS __attribute__((address_space(3)))
; __device__ __forceinline__ float rsqrtf_(float x) { return __builtin_amdgcn_rsqf(x); }
;     __device__ bool next(int i, Unit& u) const {
;         const long L = (long)i * G + c; if (L >= nwg) return false;
;         int wgid = (int)L; { const int q = nwg / NXCD, r = nwg % NXCD, xcd = wgid % NXCD, off = wgid / NXCD; wgid = (xcd < r ? xcd * (q + 1) : r * (q + 1) + (xcd - r) * q) + off; }
;         const int nig = WGM * nN, gid = wgid / nig, fm = gid * WGM, gsz = (nM - fm) < WGM ? (nM - fm) : WGM;
;         u.pm = fm + ((wgid % nig) % gsz); u.pn = (wgid % nig) / gsz; return true;
;     }
;     __device__ static __forceinline__ float rstd_of(const float* ssq, int row) {
;         const f32x4 a = *(const f32x4*)(ssq + (size_t)row * 16), b = *(const f32x4*)(ssq + (size_t)row * 16 + 4), c = *(const f32x4*)(ssq + (size_t)row * 16 + 8), d = *(const f32x4*)(ssq + (size_t)row * 16 + 12);
;         const float s = ((a.x + a.y) + (a.z + a.w)) + ((b.x + b.y) + (b.z + b.w)) + ((c.x + c.y) + (c.z + c.w)) + ((d.x + d.y) + (d.z + d.w));
;         return rsqrtf_(s * (1.0f / D) + EPS);
;     }
;     template <class Order>
;     __device__ static __forceinline__ void rstd_prologue(const float* ssq, const Order& S, int tid) {
;         LAS float* rsl = (LAS float*)((LAS unsigned char*)0 + pg8::STAGE_BYTES);
;         const int wv = __builtin_amdgcn_readfirstlane(tid >> 8), r = tid & 255;
;         float rs[4]; bool ok[4];
; #pragma unroll
;         for (int k = 0; k < 4; ++k) { pg8::Unit u; ok[k] = S.next(2 * k + wv, u); rs[k] = ok[k] ? rstd_of(ssq, u.pm * 256 + r) : 0.f; }
.LBB0_1874:
	s_ashr_i32 s2, s4, 3
	s_add_i32 s2, s6, s2
	s_mul_hi_i32 s3, s2, 0x3e0f83e1
	s_lshr_b32 s4, s3, 31
	s_ashr_i32 s3, s3, 5
	s_add_i32 s3, s3, s4
	s_mul_i32 s4, s3, 0x84
	s_sub_i32 s2, s2, s4
	s_mul_i32 s3, s3, 6
	v_readlane_b32 s4, v255, 25
	s_sub_i32 s4, s4, s3
	s_min_i32 s4, s4, 6
	s_abs_i32 s4, s4
	v_cvt_f32_u32_e32 v3, s4
	s_sub_i32 s6, 0, s4
	s_ashr_i32 s5, s2, 31
	s_abs_i32 s2, s2
	v_rcp_iflag_f32_e32 v3, v3
	s_nop 0
	v_mul_f32_e32 v3, 0x4f7ffffe, v3
	v_cvt_u32_f32_e32 v3, v3
	s_nop 0
	v_readfirstlane_b32 s7, v3
	s_mul_i32 s6, s6, s7
	s_mul_hi_u32 s6, s7, s6
	s_add_i32 s7, s7, s6
	s_mul_hi_u32 s6, s2, s7
	s_mul_i32 s6, s6, s4
	s_sub_i32 s2, s2, s6
	s_sub_i32 s6, s2, s4
	s_cmp_ge_u32 s2, s4
	s_cselect_b32 s2, s6, s2
	s_sub_i32 s6, s2, s4
	s_cmp_ge_u32 s2, s4
	s_cselect_b32 s2, s6, s2
	s_xor_b32 s2, s2, s5
	s_sub_i32 s2, s2, s5
	s_add_i32 s3, s3, s2
	v_lshl_or_b32 v26, s3, 8, v2
	v_ashrrev_i32_e32 v27, 31, v26
	v_readlane_b32 s2, v249, 26
	v_lshlrev_b64 v[26:27], 6, v[26:27]
	v_readlane_b32 s3, v249, 27
	s_nop 1
	v_lshl_add_u64 v[38:39], s[2:3], 0, v[26:27]
	global_load_dwordx4 v[26:29], v[38:39], off offset:48
	global_load_dwordx4 v[30:33], v[38:39], off offset:32
	global_load_dwordx4 v[34:37], v[38:39], off offset:16
	s_nop 0
	global_load_dwordx4 v[38:41], v[38:39], off

; #define LAS __attribute__((address_space(3)))
; __device__ __forceinline__ float rsqrtf_(float x) { return __builtin_amdgcn_rsqf(x); }
;     __device__ bool next(int i, Unit& u) const {
;         const long L = (long)i * G + c; if (L >= nwg) return false;
;         int wgid = (int)L; { const int q = nwg / NXCD, r = nwg % NXCD, xcd = wgid % NXCD, off = wgid / NXCD; wgid = (xcd < r ? xcd * (q + 1) : r * (q + 1) + (xcd - r) * q) + off; }
;         const int nig = WGM * nN, gid = wgid / nig, fm = gid * WGM, gsz = (nM - fm) < WGM ? (nM - fm) : WGM;
;         u.pm = fm + ((wgid % nig) % gsz); u.pn = (wgid % nig) / gsz; return true;
;     }
;     __device__ static __forceinline__ float rstd_of(const float* ssq, int row) {
;         const f32x4 a = *(const f32x4*)(ssq + (size_t)row * 16), b = *(const f32x4*)(ssq + (size_t)row * 16 + 4), c = *(const f32x4*)(ssq + (size_t)row * 16 + 8), d = *(const f32x4*)(ssq + (size_t)row * 16 + 12);
;         const float s = ((a.x + a.y) + (a.z + a.w)) + ((b.x + b.y) + (b.z + b.w)) + ((c.x + c.y) + (c.z + c.w)) + ((d.x + d.y) + (d.z + d.w));
;         return rsqrtf_(s * (1.0f / D) + EPS);
;     }
;     template <class Order>
;     __device__ static __forceinline__ void rstd_prologue(const float* ssq, const Order& S, int tid) {
;         LAS float* rsl = (LAS float*)((LAS unsigned char*)0 + pg8::STAGE_BYTES);
;         const int wv = __builtin_amdgcn_readfirstlane(tid >> 8), r = tid & 255;
;         float rs[4]; bool ok[4];
; #pragma unroll
;         for (int k = 0; k < 4; ++k) { pg8::Unit u; ok[k] = S.next(2 * k + wv, u); rs[k] = ok[k] ? rstd_of(ssq, u.pm * 256 + r) : 0.f; }
.LBB0_1880:
	s_ashr_i32 s4, s6, 3
	s_add_i32 s4, s27, s4
	s_mul_hi_i32 s5, s4, 0x3e0f83e1
	s_lshr_b32 s6, s5, 31
	s_ashr_i32 s5, s5, 5
	s_add_i32 s5, s5, s6
	s_mul_i32 s6, s5, 0x84
	s_sub_i32 s4, s4, s6
	s_mul_i32 s5, s5, 6
	v_readlane_b32 s6, v255, 25
	s_sub_i32 s6, s6, s5
	s_min_i32 s6, s6, 6
	s_abs_i32 s6, s6
	v_cvt_f32_u32_e32 v4, s6
	s_sub_i32 s27, 0, s6
	s_ashr_i32 s7, s4, 31
	s_abs_i32 s4, s4
	v_rcp_iflag_f32_e32 v4, v4
	s_nop 0
	v_mul_f32_e32 v4, 0x4f7ffffe, v4
	v_cvt_u32_f32_e32 v4, v4
	s_nop 0
	v_readfirstlane_b32 s28, v4
	s_mul_i32 s27, s27, s28
	s_mul_hi_u32 s27, s28, s27
	s_add_i32 s28, s28, s27
	s_mul_hi_u32 s27, s4, s28
	s_mul_i32 s27, s27, s6
	s_sub_i32 s4, s4, s27
	s_sub_i32 s27, s4, s6
	s_cmp_ge_u32 s4, s6
	s_cselect_b32 s4, s27, s4
	s_sub_i32 s27, s4, s6
	s_cmp_ge_u32 s4, s6
	s_cselect_b32 s4, s27, s4
	s_xor_b32 s4, s4, s7
	s_sub_i32 s4, s4, s7
	s_add_i32 s5, s5, s4
	v_lshl_or_b32 v44, s5, 8, v2
	v_ashrrev_i32_e32 v45, 31, v44
	v_readlane_b32 s4, v249, 26
	v_lshlrev_b64 v[44:45], 6, v[44:45]
	v_readlane_b32 s5, v249, 27
	s_nop 1
	v_lshl_add_u64 v[56:57], s[4:5], 0, v[44:45]
	global_load_dwordx4 v[44:47], v[56:57], off offset:48
	global_load_dwordx4 v[48:51], v[56:57], off offset:32
	global_load_dwordx4 v[52:55], v[56:57], off offset:16
	s_nop 0
	global_load_dwordx4 v[56:59], v[56:57], off

; #define LAS __attribute__((address_space(3)))
; __device__ __forceinline__ float rsqrtf_(float x) { return __builtin_amdgcn_rsqf(x); }
;     __device__ bool next(int i, Unit& u) const {
;         const long L = (long)i * G + c; if (L >= nwg) return false;
;         int wgid = (int)L; { const int q = nwg / NXCD, r = nwg % NXCD, xcd = wgid % NXCD, off = wgid / NXCD; wgid = (xcd < r ? xcd * (q + 1) : r * (q + 1) + (xcd - r) * q) + off; }
;         const int nig = WGM * nN, gid = wgid / nig, fm = gid * WGM, gsz = (nM - fm) < WGM ? (nM - fm) : WGM;
;         u.pm = fm + ((wgid % nig) % gsz); u.pn = (wgid % nig) / gsz; return true;
;     }
;     __device__ static __forceinline__ float rstd_of(const float* ssq, int row) {
;         const f32x4 a = *(const f32x4*)(ssq + (size_t)row * 16), b = *(const f32x4*)(ssq + (size_t)row * 16 + 4), c = *(const f32x4*)(ssq + (size_t)row * 16 + 8), d = *(const f32x4*)(ssq + (size_t)row * 16 + 12);
;         const float s = ((a.x + a.y) + (a.z + a.w)) + ((b.x + b.y) + (b.z + b.w)) + ((c.x + c.y) + (c.z + c.w)) + ((d.x + d.y) + (d.z + d.w));
;         return rsqrtf_(s * (1.0f / D) + EPS);
;     }
;     template <class Order>
;     __device__ static __forceinline__ void rstd_prologue(const float* ssq, const Order& S, int tid) {
;         LAS float* rsl = (LAS float*)((LAS unsigned char*)0 + pg8::STAGE_BYTES);
;         const int wv = __builtin_amdgcn_readfirstlane(tid >> 8), r = tid & 255;
;         float rs[4]; bool ok[4];
; #pragma unroll
;         for (int k = 0; k < 4; ++k) { pg8::Unit u; ok[k] = S.next(2 * k + wv, u); rs[k] = ok[k] ? rstd_of(ssq, u.pm * 256 + r) : 0.f; }
.LBB0_1886:
	s_ashr_i32 s6, s27, 3
	s_add_i32 s6, s30, s6
	s_mul_hi_i32 s7, s6, 0x3e0f83e1
	s_lshr_b32 s27, s7, 31
	s_ashr_i32 s7, s7, 5
	s_add_i32 s7, s7, s27
	s_mul_i32 s27, s7, 0x84
	s_mul_i32 s7, s7, 6
	v_readlane_b32 s11, v255, 25
	s_sub_i32 s6, s6, s27
	s_sub_i32 s27, s11, s7
	s_min_i32 s27, s27, 6
	s_abs_i32 s27, s27
	v_cvt_f32_u32_e32 v5, s27
	s_sub_i32 s30, 0, s27
	s_ashr_i32 s28, s6, 31
	s_abs_i32 s6, s6
	v_rcp_iflag_f32_e32 v5, v5
	s_nop 0
	v_mul_f32_e32 v5, 0x4f7ffffe, v5
	v_cvt_u32_f32_e32 v5, v5
	s_nop 0
	v_readfirstlane_b32 s31, v5
	s_mul_i32 s30, s30, s31
	s_mul_hi_u32 s30, s31, s30
	s_add_i32 s31, s31, s30
	s_mul_hi_u32 s30, s6, s31
	s_mul_i32 s30, s30, s27
	s_sub_i32 s6, s6, s30
	s_sub_i32 s30, s6, s27
	s_cmp_ge_u32 s6, s27
	s_cselect_b32 s6, s30, s6
	s_sub_i32 s30, s6, s27
	s_cmp_ge_u32 s6, s27
	s_cselect_b32 s6, s30, s6
	s_xor_b32 s6, s6, s28
	s_sub_i32 s6, s6, s28
	s_add_i32 s7, s7, s6
	v_lshl_or_b32 v62, s7, 8, v2
	v_ashrrev_i32_e32 v63, 31, v62
	v_readlane_b32 s6, v249, 26
	v_lshlrev_b64 v[62:63], 6, v[62:63]
	v_readlane_b32 s7, v249, 27
	s_nop 1
	v_lshl_add_u64 v[74:75], s[6:7], 0, v[62:63]
	global_load_dwordx4 v[62:65], v[74:75], off offset:48
	global_load_dwordx4 v[66:69], v[74:75], off offset:32
	global_load_dwordx4 v[70:73], v[74:75], off offset:16
	s_nop 0
	global_load_dwordx4 v[74:77], v[74:75], off

; #define LAS __attribute__((address_space(3)))
; __device__ __forceinline__ float rsqrtf_(float x) { return __builtin_amdgcn_rsqf(x); }
;     __device__ bool next(int i, Unit& u) const {
;         const long L = (long)i * G + c; if (L >= nwg) return false;
;         int wgid = (int)L; { const int q = nwg / NXCD, r = nwg % NXCD, xcd = wgid % NXCD, off = wgid / NXCD; wgid = (xcd < r ? xcd * (q + 1) : r * (q + 1) + (xcd - r) * q) + off; }
;         const int nig = WGM * nN, gid = wgid / nig, fm = gid * WGM, gsz = (nM - fm) < WGM ? (nM - fm) : WGM;
;         u.pm = fm + ((wgid % nig) % gsz); u.pn = (wgid % nig) / gsz; return true;
;     }
;     __device__ static __forceinline__ float rstd_of(const float* ssq, int row) {
;         const f32x4 a = *(const f32x4*)(ssq + (size_t)row * 16), b = *(const f32x4*)(ssq + (size_t)row * 16 + 4), c = *(const f32x4*)(ssq + (size_t)row * 16 + 8), d = *(const f32x4*)(ssq + (size_t)row * 16 + 12);
;         const float s = ((a.x + a.y) + (a.z + a.w)) + ((b.x + b.y) + (b.z + b.w)) + ((c.x + c.y) + (c.z + c.w)) + ((d.x + d.y) + (d.z + d.w));
;         return rsqrtf_(s * (1.0f / D) + EPS);
;     }
;     template <class Order>
;     __device__ static __forceinline__ void rstd_prologue(const float* ssq, const Order& S, int tid) {
;         LAS float* rsl = (LAS float*)((LAS unsigned char*)0 + pg8::STAGE_BYTES);
;         const int wv = __builtin_amdgcn_readfirstlane(tid >> 8), r = tid & 255;
;         float rs[4]; bool ok[4];
; #pragma unroll
;         for (int k = 0; k < 4; ++k) { pg8::Unit u; ok[k] = S.next(2 * k + wv, u); rs[k] = ok[k] ? rstd_of(ssq, u.pm * 256 + r) : 0.f; }
; #pragma unroll
;         for (int k = 0; k < 4; ++k) if (ok[k]) rsl[(2 * k + wv) * 256 + r] = rs[k];
.LBB0_1892:
	s_ashr_i32 s17, s17, 3
	s_add_i32 s17, s28, s17
	s_mul_hi_i32 s27, s17, 0x3e0f83e1
	s_lshr_b32 s28, s27, 31
	s_ashr_i32 s27, s27, 5
	s_add_i32 s27, s27, s28
	s_mul_i32 s28, s27, 0x84
	s_mul_i32 s27, s27, 6
	v_readlane_b32 s11, v255, 25
	s_sub_i32 s17, s17, s28
	s_sub_i32 s28, s11, s27
	s_min_i32 s28, s28, 6
	s_abs_i32 s28, s28
	v_cvt_f32_u32_e32 v6, s28
	s_sub_i32 s31, 0, s28
	s_ashr_i32 s30, s17, 31
	s_abs_i32 s17, s17
	v_rcp_iflag_f32_e32 v6, v6
	s_nop 0
	v_mul_f32_e32 v6, 0x4f7ffffe, v6
	v_cvt_u32_f32_e32 v6, v6
	s_nop 0
	v_readfirstlane_b32 s62, v6
	s_mul_i32 s31, s31, s62
	s_mul_hi_u32 s31, s62, s31
	s_add_i32 s62, s62, s31
	s_mul_hi_u32 s31, s17, s62
	s_mul_i32 s31, s31, s28
	s_sub_i32 s17, s17, s31
	s_sub_i32 s31, s17, s28
	s_cmp_ge_u32 s17, s28
	s_cselect_b32 s17, s31, s17
	s_sub_i32 s31, s17, s28
	s_cmp_ge_u32 s17, s28
	s_cselect_b32 s17, s31, s17
	s_xor_b32 s17, s17, s30
	s_sub_i32 s17, s17, s30
	s_add_i32 s27, s27, s17
	v_lshl_or_b32 v80, s27, 8, v2
	v_ashrrev_i32_e32 v81, 31, v80
	v_readlane_b32 s30, v249, 26
	v_lshlrev_b64 v[80:81], 6, v[80:81]
	v_readlane_b32 s31, v249, 27
	s_nop 1
	v_lshl_add_u64 v[92:93], s[30:31], 0, v[80:81]
	global_load_dwordx4 v[80:83], v[92:93], off offset:48
	global_load_dwordx4 v[84:87], v[92:93], off offset:32
	global_load_dwordx4 v[88:91], v[92:93], off offset:16
	s_nop 0
	global_load_dwordx4 v[92:95], v[92:93], off
.LBB0_1893:
	s_waitcnt vmcnt(0)
	s_andn2_b64 vcc, exec, s[0:1]
	s_cbranch_vccnz .Lrs2_0
	v_add_f32_e32 v30, v30, v31
	v_add_f32_e32 v32, v32, v33
	v_mov_b32_e32 v42, v39
	v_mov_b32_e32 v43, v40
	v_mov_b32_e32 v39, v41
	v_mov_b32_e32 v40, v35
	v_mov_b32_e32 v41, v36
	v_mov_b32_e32 v35, v37
	v_pk_add_f32 v[38:39], v[42:43], v[38:39]
	v_pk_add_f32 v[34:35], v[40:41], v[34:35]
	v_pk_add_f32 v[38:39], v[38:39], v[38:39] op_sel:[0,1] op_sel_hi:[1,0]
	v_pk_add_f32 v[34:35], v[34:35], v[34:35] op_sel:[0,1] op_sel_hi:[1,0]
	v_mov_b32_e32 v39, v26
	v_mov_b32_e32 v35, v27
	v_mov_b32_e32 v31, v28
	v_mov_b32_e32 v33, v29
	v_pk_add_f32 v[26:27], v[38:39], v[34:35]
	v_pk_add_f32 v[28:29], v[30:31], v[32:33]
	s_nop 0
	v_pk_add_f32 v[26:27], v[26:27], v[28:29]
	s_nop 0
	v_add_f32_e32 v3, v26, v27
	v_fmamk_f32 v3, v3, 0x3a800000, v204
	v_rsq_f32_e32 v3, v3
.Lrs2_0:
	s_andn2_b64 vcc, exec, s[2:3]
	s_cbranch_vccnz .Lrs2_1
	v_add_f32_e32 v48, v48, v49
	v_add_f32_e32 v50, v50, v51
	v_mov_b32_e32 v60, v57
	v_mov_b32_e32 v61, v58
	v_mov_b32_e32 v57, v59
	v_mov_b32_e32 v58, v53
	v_mov_b32_e32 v59, v54
	v_mov_b32_e32 v53, v55
	v_pk_add_f32 v[56:57], v[60:61], v[56:57]
	v_pk_add_f32 v[52:53], v[58:59], v[52:53]
	v_pk_add_f32 v[56:57], v[56:57], v[56:57] op_sel:[0,1] op_sel_hi:[1,0]
	v_pk_add_f32 v[52:53], v[52:53], v[52:53] op_sel:[0,1] op_sel_hi:[1,0]
	v_mov_b32_e32 v57, v44
	v_mov_b32_e32 v53, v45
	v_mov_b32_e32 v49, v46
	v_mov_b32_e32 v51, v47
	v_pk_add_f32 v[44:45], v[56:57], v[52:53]
	v_pk_add_f32 v[46:47], v[48:49], v[50:51]
	s_nop 0
	v_pk_add_f32 v[44:45], v[44:45], v[46:47]
	s_nop 0
	v_add_f32_e32 v4, v44, v45
	v_fmamk_f32 v4, v4, 0x3a800000, v204
	v_rsq_f32_e32 v4, v4
.Lrs2_1:
	s_andn2_b64 vcc, exec, s[4:5]
	s_cbranch_vccnz .Lrs2_2
	v_add_f32_e32 v66, v66, v67
	v_add_f32_e32 v68, v68, v69
	v_mov_b32_e32 v78, v75
	v_mov_b32_e32 v79, v76
	v_mov_b32_e32 v75, v77
	v_mov_b32_e32 v76, v71
	v_mov_b32_e32 v77, v72
	v_mov_b32_e32 v71, v73
	v_pk_add_f32 v[74:75], v[78:79], v[74:75]
	v_pk_add_f32 v[70:71], v[76:77], v[70:71]
	v_pk_add_f32 v[74:75], v[74:75], v[74:75] op_sel:[0,1] op_sel_hi:[1,0]
	v_pk_add_f32 v[70:71], v[70:71], v[70:71] op_sel:[0,1] op_sel_hi:[1,0]
	v_mov_b32_e32 v75, v62
	v_mov_b32_e32 v71, v63
	v_mov_b32_e32 v67, v64
	v_mov_b32_e32 v69, v65
	v_pk_add_f32 v[62:63], v[74:75], v[70:71]
	v_pk_add_f32 v[64:65], v[66:67], v[68:69]
	s_nop 0
	v_pk_add_f32 v[62:63], v[62:63], v[64:65]
	s_nop 0
	v_add_f32_e32 v5, v62, v63
	v_fmamk_f32 v5, v5, 0x3a800000, v204
	v_rsq_f32_e32 v5, v5
.Lrs2_2:
	s_andn2_b64 vcc, exec, s[6:7]
	s_cbranch_vccnz .Lrs2_3
	v_add_f32_e32 v84, v84, v85
	v_add_f32_e32 v86, v86, v87
	v_mov_b32_e32 v96, v93
	v_mov_b32_e32 v97, v94
	v_mov_b32_e32 v93, v95
	v_mov_b32_e32 v94, v89
	v_mov_b32_e32 v95, v90
	v_mov_b32_e32 v89, v91
	v_pk_add_f32 v[92:93], v[96:97], v[92:93]
	v_pk_add_f32 v[88:89], v[94:95], v[88:89]
	v_pk_add_f32 v[92:93], v[92:93], v[92:93] op_sel:[0,1] op_sel_hi:[1,0]
	v_pk_add_f32 v[88:89], v[88:89], v[88:89] op_sel:[0,1] op_sel_hi:[1,0]
	v_mov_b32_e32 v93, v80
	v_mov_b32_e32 v89, v81
	v_mov_b32_e32 v85, v82
	v_mov_b32_e32 v87, v83
	v_pk_add_f32 v[80:81], v[92:93], v[88:89]
	v_pk_add_f32 v[82:83], v[84:85], v[86:87]
	s_nop 0
	v_pk_add_f32 v[80:81], v[80:81], v[82:83]
	s_nop 0
	v_add_f32_e32 v6, v80, v81
	v_fmamk_f32 v6, v6, 0x3a800000, v204
	v_rsq_f32_e32 v6, v6
